# compress-item GEMM loop: ds_read fragments double-buffered one K-substep ahead with counted lgkmcnt waits
# baseline (speedup 1.0000x reference)
; #define GEMM_GLOAD(P, kt_) { GEMM_GL1(P, 0, kt_) GEMM_GL1(P, 1, kt_) GEMM_GL1(P, 2, kt_) GEMM_GL1(P, 3, kt_) }
; #define GEMM_LSTORE(P, buf_) { GEMM_LS1(P, 0, buf_) GEMM_LS1(P, 1, buf_) GEMM_LS1(P, 2, buf_) GEMM_LS1(P, 3, buf_) }
; template <bool DEEP>
; DI void gemm_mainloop_t(const u16* __restrict__ Ag, int lda, const u16* __restrict__ Bg, int ldb, int K, char* ldsraw,
;                         f32x16 (&acc)[2][2], int akstep) {
;     ...
;     for (int kt = 0; kt < nk; kt += 2) {
;       if (kt + 2 < nk) GEMM_GLOAD(x, kt + 2);
;       GEMM_COMPUTE(0);
;       GEMM_LSTORE(y, 1);
;       __syncthreads();
;       if (kt + 3 < nk) GEMM_GLOAD(y, kt + 3);
;       GEMM_COMPUTE(1);
;       if (kt + 2 < nk) GEMM_LSTORE(x, 0);
;       __syncthreads();
;     }
.LBB0_423:
	s_setprio 1
	ds_read_b128 v[182:185], v171 offset:36864
	ds_read_b128 v[186:189], v170 offset:0
	ds_read_b128 v[190:193], v171 offset:41472
	ds_read_b128 v[228:231], v170 offset:4608
	ds_read_b128 v[232:235], v171 offset:36896
	ds_read_b128 v[236:239], v170 offset:32
	ds_read_b128 v[240:243], v171 offset:41504
	ds_read_b128 v[244:247], v170 offset:4640
	s_waitcnt lgkmcnt(6)
	v_mfma_f32_32x32x16_f16 v[50:65], v[182:185], v[186:189], v[50:65]
	s_waitcnt lgkmcnt(5)
	v_mfma_f32_32x32x16_f16 v[34:49], v[190:193], v[186:189], v[34:49]
	s_waitcnt lgkmcnt(4)
	v_mfma_f32_32x32x16_f16 v[18:33], v[182:185], v[228:231], v[18:33]
	v_mfma_f32_32x32x16_f16 v[2:17], v[190:193], v[228:231], v[2:17]
	ds_read_b128 v[182:185], v171 offset:36928
	ds_read_b128 v[186:189], v170 offset:64
	ds_read_b128 v[190:193], v171 offset:41536
	ds_read_b128 v[228:231], v170 offset:4672
	s_waitcnt lgkmcnt(6)
	v_mfma_f32_32x32x16_f16 v[50:65], v[232:235], v[236:239], v[50:65]
	s_waitcnt lgkmcnt(5)
	v_mfma_f32_32x32x16_f16 v[34:49], v[240:243], v[236:239], v[34:49]
	s_waitcnt lgkmcnt(4)
	v_mfma_f32_32x32x16_f16 v[18:33], v[232:235], v[244:247], v[18:33]
	v_mfma_f32_32x32x16_f16 v[2:17], v[240:243], v[244:247], v[2:17]
	ds_read_b128 v[232:235], v171 offset:36960
	ds_read_b128 v[236:239], v170 offset:96
	ds_read_b128 v[240:243], v171 offset:41568
	ds_read_b128 v[244:247], v170 offset:4704
	s_waitcnt lgkmcnt(6)
	v_mfma_f32_32x32x16_f16 v[50:65], v[182:185], v[186:189], v[50:65]
	s_waitcnt lgkmcnt(5)
	v_mfma_f32_32x32x16_f16 v[34:49], v[190:193], v[186:189], v[34:49]
	s_waitcnt lgkmcnt(4)
	v_mfma_f32_32x32x16_f16 v[18:33], v[182:185], v[228:231], v[18:33]
	v_mfma_f32_32x32x16_f16 v[2:17], v[190:193], v[228:231], v[2:17]
	s_waitcnt lgkmcnt(2)
	v_mfma_f32_32x32x16_f16 v[50:65], v[232:235], v[236:239], v[50:65]
	s_waitcnt lgkmcnt(1)
	v_mfma_f32_32x32x16_f16 v[34:49], v[240:243], v[236:239], v[34:49]
	s_waitcnt lgkmcnt(0)
	v_mfma_f32_32x32x16_f16 v[18:33], v[232:235], v[244:247], v[18:33]
	v_mfma_f32_32x32x16_f16 v[2:17], v[240:243], v[244:247], v[2:17]
	s_setprio 0
	s_cmp_gt_u32 s21, 28
	s_waitcnt vmcnt(6)
	ds_write_b128 v168, v[114:117] offset:18432
	s_waitcnt vmcnt(1)
	ds_write_b128 v168, v[150:153] offset:55296
	s_waitcnt vmcnt(5)
	ds_write_b128 v169, v[122:125] offset:18432
	s_waitcnt vmcnt(4)
	ds_write_b128 v169, v[130:133] offset:55296
	s_waitcnt vmcnt(2)
	ds_write_b128 v179, v[138:141] offset:18432
	ds_write_b128 v179, v[146:149] offset:55296
	s_waitcnt vmcnt(1)
	ds_write_b128 v180, v[154:157] offset:18432
	s_waitcnt vmcnt(0)
	ds_write_b128 v180, v[158:161] offset:55296
	s_waitcnt lgkmcnt(0)
	s_barrier
	s_cbranch_scc1 .LBB0_425
	v_add_co_u32_e32 v114, vcc, 0x9000, v174
	s_nop 1
	v_addc_co_u32_e32 v115, vcc, 0, v175, vcc
	v_add_co_u32_e32 v122, vcc, 0x669000, v174
	s_nop 1
	v_addc_co_u32_e32 v123, vcc, 0, v175, vcc
	v_add_co_u32_e32 v130, vcc, 0x20000, v172
	global_load_dwordx4 v[114:117], v[114:115], off offset:2304
	s_nop 0
	global_load_dwordx4 v[122:125], v[122:123], off offset:2304
	v_addc_co_u32_e32 v131, vcc, 0, v173, vcc
	v_add_co_u32_e32 v138, vcc, 0xcc9000, v174
	global_load_dwordx4 v[130:133], v[130:131], off offset:384
	s_nop 0
	v_addc_co_u32_e32 v139, vcc, 0, v175, vcc
	v_add_co_u32_e32 v146, vcc, 0x40000, v172
	global_load_dwordx4 v[138:141], v[138:139], off offset:2304
	s_nop 0
	v_addc_co_u32_e32 v147, vcc, 0, v173, vcc
	v_add_co_u32_e32 v150, vcc, 0x1329000, v174
	global_load_dwordx4 v[146:149], v[146:147], off offset:384
	s_nop 0
	v_addc_co_u32_e32 v151, vcc, 0, v175, vcc
	v_add_co_u32_e32 v158, vcc, 0x60000, v172
	global_load_dwordx4 v[154:157], v[150:151], off offset:2304
	s_nop 0
	v_addc_co_u32_e32 v159, vcc, 0, v173, vcc
	global_load_dwordx4 v[150:153], v[172:173], off offset:384
	s_nop 0
	global_load_dwordx4 v[158:161], v[158:159], off offset:384
.LBB0_425:
	s_setprio 1
	ds_read_b128 v[182:185], v171 offset:55296
	ds_read_b128 v[186:189], v170 offset:18432
	ds_read_b128 v[190:193], v171 offset:59904
	ds_read_b128 v[228:231], v170 offset:23040
	ds_read_b128 v[232:235], v171 offset:55328
	ds_read_b128 v[236:239], v170 offset:18464
	ds_read_b128 v[240:243], v171 offset:59936
	ds_read_b128 v[244:247], v170 offset:23072
	s_waitcnt lgkmcnt(6)
	v_mfma_f32_32x32x16_f16 v[50:65], v[182:185], v[186:189], v[50:65]
	s_waitcnt lgkmcnt(5)
	v_mfma_f32_32x32x16_f16 v[34:49], v[190:193], v[186:189], v[34:49]
	s_waitcnt lgkmcnt(4)
	v_mfma_f32_32x32x16_f16 v[18:33], v[182:185], v[228:231], v[18:33]
	v_mfma_f32_32x32x16_f16 v[2:17], v[190:193], v[228:231], v[2:17]
	ds_read_b128 v[182:185], v171 offset:55360
	ds_read_b128 v[186:189], v170 offset:18496
	ds_read_b128 v[190:193], v171 offset:59968
	ds_read_b128 v[228:231], v170 offset:23104
	s_waitcnt lgkmcnt(6)
	v_mfma_f32_32x32x16_f16 v[50:65], v[232:235], v[236:239], v[50:65]
	s_waitcnt lgkmcnt(5)
	v_mfma_f32_32x32x16_f16 v[34:49], v[240:243], v[236:239], v[34:49]
	s_waitcnt lgkmcnt(4)
	v_mfma_f32_32x32x16_f16 v[18:33], v[232:235], v[244:247], v[18:33]
	v_mfma_f32_32x32x16_f16 v[2:17], v[240:243], v[244:247], v[2:17]
	ds_read_b128 v[232:235], v171 offset:55392
	ds_read_b128 v[236:239], v170 offset:18528
	ds_read_b128 v[240:243], v171 offset:60000
	ds_read_b128 v[244:247], v170 offset:23136
	s_waitcnt lgkmcnt(6)
	v_mfma_f32_32x32x16_f16 v[50:65], v[182:185], v[186:189], v[50:65]
	s_waitcnt lgkmcnt(5)
	v_mfma_f32_32x32x16_f16 v[34:49], v[190:193], v[186:189], v[34:49]
	s_waitcnt lgkmcnt(4)
	v_mfma_f32_32x32x16_f16 v[18:33], v[182:185], v[228:231], v[18:33]
	v_mfma_f32_32x32x16_f16 v[2:17], v[190:193], v[228:231], v[2:17]
	s_waitcnt lgkmcnt(2)
	v_mfma_f32_32x32x16_f16 v[50:65], v[232:235], v[236:239], v[50:65]
	s_waitcnt lgkmcnt(1)
	v_mfma_f32_32x32x16_f16 v[34:49], v[240:243], v[236:239], v[34:49]
	s_waitcnt lgkmcnt(0)
	v_mfma_f32_32x32x16_f16 v[18:33], v[232:235], v[244:247], v[18:33]
	v_mfma_f32_32x32x16_f16 v[2:17], v[240:243], v[244:247], v[2:17]
	s_setprio 0
	s_andn2_b64 vcc, exec, s[14:15]
	s_cbranch_vccnz .LBB0_420
	ds_write_b128 v168, v[98:101]
	ds_write_b128 v168, v[118:121] offset:36864
	ds_write_b128 v169, v[102:105]
	ds_write_b128 v169, v[106:109] offset:36864
	ds_write_b128 v179, v[110:113]
	ds_write_b128 v179, v[126:129] offset:36864
	ds_write_b128 v180, v[134:137]
	ds_write_b128 v180, v[142:145] offset:36864
	s_branch .LBB0_420
